# v60 with the barrier spin caps raised (early L1 invalidate + flat barrier + write-through residual-output stores)
# baseline (speedup 1.0000x reference)
.Lxbf_0_spin:
	global_load_dword v5, v2, s[8:9] offset:1024 sc1
	s_waitcnt vmcnt(0)
	v_cmp_ge_u32_e32 vcc, v5, v4
	s_cbranch_vccnz .Lxbf_0_done
	s_sleep 1
	s_add_i32 s28, s28, 1
	s_cmp_lt_u32 s28, 0x200000
	s_cbranch_scc1 .Lxbf_0_spin
